# LDS bank conflicts: bias-table shifted copies re-strided (968->972, 768->772 words) so the four copies land on different bank quads
# speedup vs baseline: 1.0010x; 1.0010x over previous
; __global__ void __launch_bounds__(NWAVES * 64, 2) fwd_kernel(Args args) {
;     ...
;             for (int i = tid; i < 4 * 968; i += NWAVES * 64) { const int sft = i / 968, k = i % 968; f32x4 v;
; #pragma unroll
;                 for (int e = 0; e < 4; ++e) { const int x = 4 * k + sft + e - 16; v[e] = (x >= 0 && x < 8 * 15 * 32 + 16) ? tab[min(max(x, 0), 8 * 15 * 32 + 15)] : 0.f; }
;                 cpy[i] = v; }
.LBB0_256:
	s_or_b64 exec, exec, s[34:35]
	s_mov_b32 vcc_lo, 0x43b3d5b
	s_waitcnt lgkmcnt(0)
	v_mul_hi_i32 v8, v7, vcc_lo
	s_movk_i32 s0, 0xd1f
	v_ashrrev_i32_e32 v8, 4, v8
	v_lshl_add_u32 v8, v8, 6, v6
	ds_write_b128 v8, v[2:5]
	v_add_u32_e32 v2, 0x200, v7
	v_cmp_lt_i32_e32 vcc, s0, v7
	v_add_u32_e32 v0, 0x800, v0
	v_add_u32_e32 v6, 0x2000, v6
	s_or_b64 s[30:31], vcc, s[30:31]
	v_mov_b32_e32 v7, v2
	s_andn2_b64 exec, exec, s[30:31]
	s_cbranch_execz .LBB0_265

; #define DMA_TILE(t) do { const unsigned sl_ = (unsigned)__builtin_amdgcn_readfirstlane(ring0 + (unsigned)(((t) + base) % 3) * SLOT); \
;         glds16kv(loffk, loffv, kg + (size_t)(t) * 64 * PITCH, vg + (size_t)(t) * 64 * PITCH, sl_); } while (0)
; #define DMA_NEXT(i) do { const unsigned sl_ = (unsigned)__builtin_amdgcn_readfirstlane(ring0 + (unsigned)((nT + (i) + base) % 3) * SLOT); \
;         glds16kv(loffk, loffv, nK + (size_t)(i) * 64 * PITCH, nV + (size_t)(i) * 64 * PITCH, sl_); } while (0)
; template <int MODE> ...
;     ...
;     int kofs[2], kad[2][2], vad[2], relm[2], bofs[2];
; #pragma unroll
;     for (int jj = 0; jj < 2; ++jj) {
;         const int j = 2 * half + jj; const int koff = (MODE == 1) ? 0 : ((j == 0) ? 0 : (j == 1) ? 8 : (j == 2) ? 24 : 32);
;         const int par = (koff >> 3) & 1, s0 = g ^ (qi >> 1);
;         kofs[jj] = koff;
;         kad[jj][0] = (koff + qi) * 128 + ((s0 ^ (4 * par)) << 4); kad[jj][1] = (koff + qi) * 128 + ((s0 ^ (4 * par) ^ 4) << 4);
;         vad[jj] = 8192 + (koff + 4 * g + va) * 128 + vb * 8;
;         const int c = 16 * j + qi, cs = min(max(c - 8, 0), 48);
;         relm[jj] = koff + 4 * g - cs;
;         const int raw = (MODE == 1) ? (ktok0 - (qtok0 + 16 * jj + qi) + 4 * g + 191) : (koff + 4 * g - c + 15 + 16); const int s4 = (3 - qi) & 3;
;         bofs[jj] = s4 * ((MODE == 0) ? 968 : 768) + ((raw - s4) >> 2); }
;     const float NEG = -INFINITY;
;     f32x4 mneg[2][2];
; #pragma unroll
;     for (int jj = 0; jj < 2; ++jj)
; #pragma unroll
;         for (int kt = 0; kt < 2; ++kt)
; #pragma unroll
;             for (int e = 0; e < 4; ++e) mneg[jj][kt][e] = (MODE == 0 && !((unsigned)(relm[jj] + 16 * kt + e) < 16u)) ? NEG : 0.f;
;     constexpr int NH = (MODE == 1) ? 2 : 1;
;     auto head = [&](const int t) __attribute__((always_inline)) {
;         if (t >= 2) { if (t + 1 < nT || nK) asm volatile("s_waitcnt vmcnt(2)" ::: "memory"); else asm volatile("s_waitcnt vmcnt(0)" ::: "memory"); }
;         __builtin_amdgcn_s_barrier();
;         if (t + 2 < nT) DMA_TILE(t + 2); else if (nK) DMA_NEXT(t + 2 - nT);
.LBB0_273:
	v_sub_u32_e64 v0, s24, 1 clamp
	v_lshlrev_b32_e32 v121, 2, v34
	v_readfirstlane_b32 s14, v0
	s_min_u32 s40, s14, 0xf8
	s_max_i32 s14, s0, 4
	s_add_i32 s14, s14, -4
	s_min_u32 s27, s14, 0xf8
	s_sub_i32 s25, s27, s0
	v_readlane_b32 s0, v254, 6
	v_add_lshl_u32 v5, v119, s95, 7
	v_lshrrev_b32_e32 v0, 2, v119
	v_xor_b32_e32 v6, s0, v119
	v_lshrrev_b32_e32 v6, 1, v6
	v_xor_b32_e32 v6, v6, v34
	v_lshlrev_b32_e32 v6, 4, v6
	v_add_u32_e32 v89, v6, v5
	v_xad_u32 v88, v6, 64, v5
	v_add_u32_e32 v5, s95, v121
	v_or_b32_e32 v6, v5, v0
	v_and_or_b32 v4, v118, 3, 28
	v_lshlrev_b32_e32 v86, 7, v6
	v_or_b32_e32 v6, s97, v119
	v_readlane_b32 s0, v254, 7
	v_sub_u32_e64 v7, v6, 8 clamp
	v_sub_u32_e32 v4, v4, v6
	v_xor_b32_e32 v8, s0, v119
	s_mul_i32 s14, s12, 0x780
	v_lshlrev_b32_e32 v3, 3, v118
	v_sub_u32_e32 v7, v5, v7
	v_add_u32_e32 v5, v4, v5
	v_lshrrev_b32_e32 v8, 1, v8
	s_add_i32 s24, s14, 0
	v_and_b32_e32 v122, 24, v3
	v_bitop3_b32 v3, v118, 3, v118 bitop3:0xc
	v_ashrrev_i32_e32 v5, 2, v5
	s_movk_i32 s14, 0x3cc
	v_xor_b32_e32 v8, v8, v34
	v_mad_u32_u24 v87, v3, s14, v5
	v_add_lshl_u32 v5, v119, s98, 7
	v_lshlrev_b32_e32 v8, 4, v8
	v_add_u32_e32 v92, v8, v5
	v_xad_u32 v91, v8, 64, v5
	v_add_u32_e32 v5, s98, v121
	v_add3_u32 v4, v4, v5, -16
	v_ashrrev_i32_e32 v4, 2, v4
	v_mad_u32_u24 v90, v3, s14, v4
	v_cmp_lt_u32_e32 vcc, 15, v7
	v_mov_b32_e32 v4, 0xff800000
	v_add_u32_e32 v3, -15, v7
	v_cndmask_b32_e32 v110, 0, v4, vcc
	v_cmp_gt_u32_e32 vcc, -16, v3
	v_add_u32_e32 v3, -14, v7
	v_or_b32_e32 v0, v5, v0
	v_cndmask_b32_e32 v111, 0, v4, vcc
	v_cmp_gt_u32_e32 vcc, -16, v3
	v_add_u32_e32 v3, -13, v7
	v_lshlrev_b32_e32 v123, 7, v0
	v_cndmask_b32_e32 v112, 0, v4, vcc
	v_cmp_gt_u32_e32 vcc, -16, v3
	v_add_u32_e32 v3, 1, v7
	v_min_u32_e32 v0, 40, v6
	v_cndmask_b32_e32 v113, 0, v4, vcc
	v_cmp_gt_u32_e32 vcc, -16, v7
	v_sub_u32_e32 v0, v5, v0
	v_add_u32_e32 v6, -8, v0
	v_cndmask_b32_e32 v108, 0, v4, vcc
	v_cmp_gt_u32_e32 vcc, -16, v3
	v_add_u32_e32 v3, 2, v7
	s_add_i32 s40, s40, 8
	v_cndmask_b32_e32 v109, 0, v4, vcc
	v_cmp_gt_u32_e32 vcc, -16, v3
	v_add_u32_e32 v3, 3, v7
	s_sub_i32 s26, s40, s23
	v_cndmask_b32_e32 v114, 0, v4, vcc
	v_cmp_gt_u32_e32 vcc, -16, v3
	v_subrev_u32_e32 v3, 23, v0
	s_sub_i32 s23, s27, s23
	v_cndmask_b32_e32 v115, 0, v4, vcc
	v_cmp_lt_u32_e32 vcc, 15, v6
	s_add_i32 s24, s24, 0x10000
	s_add_i32 s25, s25, 7
	v_cndmask_b32_e32 v102, 0, v4, vcc
	v_cmp_gt_u32_e32 vcc, -16, v3
	v_subrev_u32_e32 v3, 22, v0
	v_bfe_u32 v120, v118, 4, 1
	v_cndmask_b32_e32 v103, 0, v4, vcc
	v_cmp_gt_u32_e32 vcc, -16, v3
	v_subrev_u32_e32 v3, 21, v0
	v_lshrrev_b32_e32 v2, 3, v119
	v_cndmask_b32_e32 v106, 0, v4, vcc
	v_cmp_gt_u32_e32 vcc, -16, v3
	v_add_u32_e32 v3, -7, v0
	s_add_i32 s41, s26, -1
	v_cndmask_b32_e32 v107, 0, v4, vcc
	v_cmp_gt_u32_e32 vcc, -16, v6
	s_cmp_lt_i32 s26, 2
	v_lshl_or_b32 v93, v120, 1, v2
	v_cndmask_b32_e32 v100, 0, v4, vcc
	v_cmp_gt_u32_e32 vcc, -16, v3
	v_add_u32_e32 v3, -6, v0
	v_add_u32_e32 v0, -5, v0
	v_cndmask_b32_e32 v101, 0, v4, vcc
	v_cmp_gt_u32_e32 vcc, -16, v3
	s_nop 1
	v_cndmask_b32_e32 v104, 0, v4, vcc
	v_cmp_gt_u32_e32 vcc, -16, v0
	s_nop 1
	v_cndmask_b32_e32 v105, 0, v4, vcc
	s_cbranch_scc1 .LBB0_280
	s_add_i32 s0, s86, 2
	s_mul_hi_u32 s14, s0, 0xaaaaaaab
	s_lshr_b32 s14, s14, 1
	s_mul_i32 s14, s14, 3
	s_sub_i32 s0, s0, s14
	s_lshl_b32 s0, s0, 14
	s_add_i32 s0, s0, s94
	s_cmp_lg_u32 s26, 2
	s_mov_b64 s[60:61], -1
	s_barrier
	s_cbranch_scc0 .LBB0_276
	s_add_u32 s52, s50, 0x90400
	s_addc_u32 s53, s51, 0
	s_add_u32 s60, s50, 0x90800
	s_addc_u32 s61, s51, 0
	s_mov_b32 m0, s0
	s_nop 0
	global_load_lds_dwordx4 v84, s[52:53]
	s_add_u32 m0, m0, 0x2000
	s_nop 0
	global_load_lds_dwordx4 v85, s[60:61]
	s_mov_b64 s[60:61], 0

; __global__ void __launch_bounds__(NWAVES * 64, 2) fwd_kernel(Args args) {
;     ...
;             for (int i = tid; i < 4 * 768; i += NWAVES * 64) { const int sft = i / 768, k = i % 768; f32x4 v;
; #pragma unroll
;                 for (int e = 0; e < 4; ++e) { const int x = 4 * k + sft + e; v[e] = (x < 8 * 384) ? tab[min(x, 8 * 384 - 1)] : -INFINITY; }
;                 cpy[i] = v; }
.LBB0_315:
	s_or_b64 exec, exec, s[34:35]
	s_mov_b32 vcc_lo, 0x2aaaaaab
	s_waitcnt lgkmcnt(0)
	v_mul_hi_i32 v23, v117, vcc_lo
	s_movk_i32 s0, 0x9ff
	v_ashrrev_i32_e32 v23, 7, v23
	v_lshl_add_u32 v23, v23, 6, v22
	ds_write_b128 v23, v[18:21]
	v_add_u32_e32 v18, 0x200, v117
	v_cmp_lt_i32_e32 vcc, s0, v117
	v_add_u32_e32 v0, 0x800, v0
	v_add_u32_e32 v22, 0x2000, v22
	s_or_b64 s[30:31], vcc, s[30:31]
	v_mov_b32_e32 v117, v18
	s_andn2_b64 exec, exec, s[30:31]
	s_cbranch_execz .LBB0_322

; template <int MODE> ...
;     ...
;     f32x4 o[2][4];
;     float mrun[2], lrun[2];
; #pragma unroll
;     for (int jj = 0; jj < 2; ++jj) {
; #pragma unroll
;         for (int dt = 0; dt < 4; ++dt) o[jj][dt] = (f32x4){0.f, 0.f, 0.f, 0.f};
;         mrun[jj] = (MODE == 1) ? sink2 : -1e30f; lrun[jj] = (MODE == 1 && g == 0) ? 1.0f : 0.0f; }
;     const int va = (lane & 15) >> 2, vb = lane & 3, sv = (2 * (g & 1) + (va >> 1)) & 3;
;     int kofs[2], kad[2][2], vad[2], relm[2], bofs[2];
; #pragma unroll
;     for (int jj = 0; jj < 2; ++jj) {
;         const int j = 2 * half + jj; const int koff = (MODE == 1) ? 0 : ((j == 0) ? 0 : (j == 1) ? 8 : (j == 2) ? 24 : 32);
;         const int par = (koff >> 3) & 1, s0 = g ^ (qi >> 1);
;         kofs[jj] = koff;
;         kad[jj][0] = (koff + qi) * 128 + ((s0 ^ (4 * par)) << 4); kad[jj][1] = (koff + qi) * 128 + ((s0 ^ (4 * par) ^ 4) << 4);
;         vad[jj] = 8192 + (koff + 4 * g + va) * 128 + vb * 8;
;         const int c = 16 * j + qi, cs = min(max(c - 8, 0), 48);
;         relm[jj] = koff + 4 * g - cs;
;         const int raw = (MODE == 1) ? (ktok0 - (qtok0 + 16 * jj + qi) + 4 * g + 191) : (koff + 4 * g - c + 15 + 16); const int s4 = (3 - qi) & 3;
;         bofs[jj] = s4 * ((MODE == 0) ? 968 : 768) + ((raw - s4) >> 2); }
.LBB0_331:
	s_min_u32 s5, s5, 0x3f40
	s_sub_i32 s5, s5, s27
	s_addk_i32 s5, 0x140
	v_lshrrev_b32_e32 v0, 2, v34
	v_lshlrev_b32_e32 v87, 2, v36
	s_ashr_i32 s5, s5, 6
	v_lshrrev_b32_e32 v3, 1, v34
	v_or_b32_e32 v0, v87, v0
	s_cmp_eq_u32 s26, 0
	v_xor_b32_e32 v3, v3, v36
	v_lshlrev_b32_e32 v72, 7, v0
	v_lshlrev_b32_e32 v0, 3, v35
	s_cselect_b64 vcc, -1, 0
	v_lshlrev_b32_e32 v4, 7, v34
	v_lshlrev_b32_e32 v3, 4, v3
	v_and_b32_e32 v73, 24, v0
	v_bitop3_b32 v0, v35, 3, v35 bitop3:0xc
	s_add_i32 s14, s24, 0xbf
	v_or_b32_e32 v86, s25, v34
	v_add_u32_e32 v70, v3, v4
	v_xad_u32 v71, v3, 64, v4
	v_add_u32_e32 v3, s14, v87
	v_add_u32_e32 v4, v86, v0
	v_sub_u32_e32 v3, v3, v4
	v_ashrrev_i32_e32 v4, 2, v3
	v_add_u32_e32 v3, -16, v3
	v_cmp_gt_u32_e64 s[36:37], 16, v35
	v_bfe_u32 v92, v35, 4, 1
	v_lshrrev_b32_e32 v2, 3, v34
	s_movk_i32 s14, 0x304
	v_ashrrev_i32_e32 v3, 2, v3
	v_cndmask_b32_e64 v88, 0, 1.0, s[36:37]
	v_mad_u32_u24 v93, v0, s14, v4
	v_mad_u32_u24 v94, v0, s14, v3
	v_lshl_or_b32 v0, v92, 1, v2
	s_add_i32 s26, s5, -1
	v_cndmask_b32_e32 v95, v91, v90, vcc
	s_cmp_lt_i32 s5, 2
	v_mov_b32_e32 v89, v88
	v_lshlrev_b32_e32 v74, 5, v0
	s_cbranch_scc1 .LBB0_347
	s_and_b32 s14, s12, 0x3fc0
	s_lshr_b32 s0, s0, 8
	s_max_u32 s14, s14, 0x80
	s_and_b32 s15, s10, 0xffffc000
	s_or_b32 s14, s14, s15
	s_and_b32 s0, s0, 1
	s_add_i32 s27, s14, 0xffffff80
	s_mulk_i32 s0, 0x1800
	v_readlane_b32 s14, v254, 53
	s_add_i32 s40, s14, s0
	s_cmp_lg_u64 s[34:35], 0
	s_cselect_b64 s[42:43], -1, 0
	s_add_i32 s41, s25, 0xffffff80
	s_add_i32 s45, s25, 0x9f
	s_add_u32 s46, s46, 0x90000
	s_addc_u32 s47, s47, 0
	s_mul_i32 s14, s5, 0xfffb8000
	s_mul_hi_i32 s0, s5, 0xfffb8000
	s_add_u32 s15, s30, s14
	s_addc_u32 s50, s31, s0
	s_add_u32 s60, s15, 0x90000
	s_addc_u32 s61, s50, 0
	s_add_u32 s14, s34, s14
	s_addc_u32 s0, s35, s0
	s_add_u32 s68, s14, 0x90000
	s_addc_u32 s69, s0, 0
	s_lshl_b32 s0, s86, 14
	v_readlane_b32 s14, v254, 62
	s_add_i32 s54, s14, s0
	s_add_i32 s64, s86, 2
	v_mov_b32_e32 v2, v1
	v_mov_b32_e32 v3, v1
	s_add_u32 s70, s70, 0x90000
	v_mov_b32_e32 v0, v1
	v_mov_b64_e32 v[52:53], v[2:3]
	v_mov_b64_e32 v[56:57], v[2:3]
	v_mov_b64_e32 v[60:61], v[2:3]
	v_mov_b64_e32 v[64:65], v[2:3]
	v_mov_b64_e32 v[36:37], v[2:3]
	v_mov_b64_e32 v[40:41], v[2:3]
	v_mov_b64_e32 v[44:45], v[2:3]
	v_mov_b64_e32 v[48:49], v[2:3]
	v_xor_b32_e32 v75, 32, v74
	v_xor_b32_e32 v76, 64, v74
	v_xor_b32_e32 v77, 0x60, v74
	v_add_u32_e32 v78, v72, v73
	v_lshlrev_b32_e32 v79, 4, v94
	v_lshlrev_b32_e32 v80, 4, v93
	s_addc_u32 s71, s71, 0
	s_mov_b32 s65, 0
	v_mov_b32_e32 v82, v95
	v_mov_b64_e32 v[50:51], v[0:1]
	v_mov_b64_e32 v[54:55], v[0:1]
	v_mov_b64_e32 v[58:59], v[0:1]
	v_mov_b64_e32 v[62:63], v[0:1]
	v_mov_b64_e32 v[34:35], v[0:1]
	v_mov_b64_e32 v[38:39], v[0:1]
	v_mov_b64_e32 v[42:43], v[0:1]
	v_mov_b64_e32 v[46:47], v[0:1]
	s_branch .LBB0_334
